# ada weight stream: 60 loads in flight per wave (was 52)
# baseline (speedup 1.0000x reference)
.LBB0_20:
	s_mul_hi_i32 s0, s7, 0x38e38e39
	s_lshr_b32 s1, s0, 31
	s_ashr_i32 s8, s0, 5
	s_add_i32 s8, s8, s1
	s_mul_i32 s0, s8, 0x90
	s_sub_i32 s0, s7, s0
	s_lshl_b32 s1, s0, 6
	v_mov_b32_e32 v2, v179
	s_and_b32 s9, s0, 7
	s_and_b32 s0, s7, 7
	s_and_b32 s1, s1, 0xfffffe00
	s_mul_i32 s14, s8, 0x2400000
	s_mul_i32 s0, s0, 0x480000
	v_add_u32_e32 v2, s1, v2
	s_mul_hi_i32 s1, s8, 0x2400000
	s_add_u32 s0, s14, s0
	v_readlane_b32 s36, v249, 0
	s_addc_u32 s1, s1, 0
	v_readlane_b32 s40, v249, 4
	v_readlane_b32 s41, v249, 5
	s_add_u32 s0, s40, s0
	v_ashrrev_i32_e32 v3, 31, v2
	s_addc_u32 s1, s41, s1
	v_lshl_add_u64 v[12:13], v[2:3], 2, s[0:1]
	s_lshl_b32 s0, s9, 9
	v_mov_b32_e32 v4, 0
	s_add_i32 s14, s0, 0
	s_mov_b64 s[0:1], 0
	v_mov_b32_e32 v5, v4
	v_mov_b32_e32 v10, v4
	v_mov_b32_e32 v11, v4
	v_mov_b32_e32 v8, v4
	v_mov_b32_e32 v9, v4
	v_mov_b32_e32 v6, v4
	v_mov_b32_e32 v7, v4
	v_readlane_b32 s37, v249, 1
	v_readlane_b32 s38, v249, 2
	v_readlane_b32 s39, v249, 3
	v_readlane_b32 s42, v249, 6
	v_readlane_b32 s43, v249, 7
	v_mov_b32_e32 v202, s14
	v_mov_b32_e32 v194, v12
	v_mov_b32_e32 v195, v13
	v_add_co_u32_e32 v196, vcc, s4, v12
	s_nop 1
	v_addc_co_u32_e32 v197, vcc, 0, v13, vcc
	v_add_co_u32_e32 v198, vcc, s5, v12
	s_nop 1
	v_addc_co_u32_e32 v199, vcc, 0, v13, vcc
	v_add_co_u32_e32 v200, vcc, s6, v12
	s_nop 1
	v_addc_co_u32_e32 v201, vcc, 0, v13, vcc
	s_mov_b32 s0, 0x24000
	s_mov_b32 s1, 0
	global_load_dword v64, v[194:195], off
	v_lshl_add_u64 v[194:195], v[194:195], 0, s[0:1]
	global_load_dword v65, v[196:197], off
	v_lshl_add_u64 v[196:197], v[196:197], 0, s[0:1]
	global_load_dword v66, v[198:199], off
	v_lshl_add_u64 v[198:199], v[198:199], 0, s[0:1]
	global_load_dword v67, v[200:201], off
	v_lshl_add_u64 v[200:201], v[200:201], 0, s[0:1]
	global_load_dword v68, v[194:195], off
	v_lshl_add_u64 v[194:195], v[194:195], 0, s[0:1]
	global_load_dword v69, v[196:197], off
	v_lshl_add_u64 v[196:197], v[196:197], 0, s[0:1]
	global_load_dword v70, v[198:199], off
	v_lshl_add_u64 v[198:199], v[198:199], 0, s[0:1]
	global_load_dword v71, v[200:201], off
	v_lshl_add_u64 v[200:201], v[200:201], 0, s[0:1]
	global_load_dword v72, v[194:195], off
	v_lshl_add_u64 v[194:195], v[194:195], 0, s[0:1]
	global_load_dword v73, v[196:197], off
	v_lshl_add_u64 v[196:197], v[196:197], 0, s[0:1]
	global_load_dword v74, v[198:199], off
	v_lshl_add_u64 v[198:199], v[198:199], 0, s[0:1]
	global_load_dword v75, v[200:201], off
	v_lshl_add_u64 v[200:201], v[200:201], 0, s[0:1]
	global_load_dword v76, v[194:195], off
	v_lshl_add_u64 v[194:195], v[194:195], 0, s[0:1]
	global_load_dword v77, v[196:197], off
	v_lshl_add_u64 v[196:197], v[196:197], 0, s[0:1]
	global_load_dword v78, v[198:199], off
	v_lshl_add_u64 v[198:199], v[198:199], 0, s[0:1]
	global_load_dword v79, v[200:201], off
	v_lshl_add_u64 v[200:201], v[200:201], 0, s[0:1]
	global_load_dword v80, v[194:195], off
	v_lshl_add_u64 v[194:195], v[194:195], 0, s[0:1]
	global_load_dword v81, v[196:197], off
	v_lshl_add_u64 v[196:197], v[196:197], 0, s[0:1]
	global_load_dword v82, v[198:199], off
	v_lshl_add_u64 v[198:199], v[198:199], 0, s[0:1]
	global_load_dword v83, v[200:201], off
	v_lshl_add_u64 v[200:201], v[200:201], 0, s[0:1]
	global_load_dword v84, v[194:195], off
	v_lshl_add_u64 v[194:195], v[194:195], 0, s[0:1]
	global_load_dword v85, v[196:197], off
	v_lshl_add_u64 v[196:197], v[196:197], 0, s[0:1]
	global_load_dword v86, v[198:199], off
	v_lshl_add_u64 v[198:199], v[198:199], 0, s[0:1]
	global_load_dword v87, v[200:201], off
	v_lshl_add_u64 v[200:201], v[200:201], 0, s[0:1]
	global_load_dword v88, v[194:195], off
	v_lshl_add_u64 v[194:195], v[194:195], 0, s[0:1]
	global_load_dword v89, v[196:197], off
	v_lshl_add_u64 v[196:197], v[196:197], 0, s[0:1]
	global_load_dword v90, v[198:199], off
	v_lshl_add_u64 v[198:199], v[198:199], 0, s[0:1]
	global_load_dword v91, v[200:201], off
	v_lshl_add_u64 v[200:201], v[200:201], 0, s[0:1]
	global_load_dword v92, v[194:195], off
	v_lshl_add_u64 v[194:195], v[194:195], 0, s[0:1]
	global_load_dword v93, v[196:197], off
	v_lshl_add_u64 v[196:197], v[196:197], 0, s[0:1]
	global_load_dword v94, v[198:199], off
	v_lshl_add_u64 v[198:199], v[198:199], 0, s[0:1]
	global_load_dword v95, v[200:201], off
	v_lshl_add_u64 v[200:201], v[200:201], 0, s[0:1]
	global_load_dword v96, v[194:195], off
	v_lshl_add_u64 v[194:195], v[194:195], 0, s[0:1]
	global_load_dword v97, v[196:197], off
	v_lshl_add_u64 v[196:197], v[196:197], 0, s[0:1]
	global_load_dword v98, v[198:199], off
	v_lshl_add_u64 v[198:199], v[198:199], 0, s[0:1]
	global_load_dword v99, v[200:201], off
	v_lshl_add_u64 v[200:201], v[200:201], 0, s[0:1]
	global_load_dword v100, v[194:195], off
	v_lshl_add_u64 v[194:195], v[194:195], 0, s[0:1]
	global_load_dword v101, v[196:197], off
	v_lshl_add_u64 v[196:197], v[196:197], 0, s[0:1]
	global_load_dword v102, v[198:199], off
	v_lshl_add_u64 v[198:199], v[198:199], 0, s[0:1]
	global_load_dword v103, v[200:201], off
	v_lshl_add_u64 v[200:201], v[200:201], 0, s[0:1]
	global_load_dword v104, v[194:195], off
	v_lshl_add_u64 v[194:195], v[194:195], 0, s[0:1]
	global_load_dword v105, v[196:197], off
	v_lshl_add_u64 v[196:197], v[196:197], 0, s[0:1]
	global_load_dword v106, v[198:199], off
	v_lshl_add_u64 v[198:199], v[198:199], 0, s[0:1]
	global_load_dword v107, v[200:201], off
	v_lshl_add_u64 v[200:201], v[200:201], 0, s[0:1]
	global_load_dword v108, v[194:195], off
	v_lshl_add_u64 v[194:195], v[194:195], 0, s[0:1]
	global_load_dword v109, v[196:197], off
	v_lshl_add_u64 v[196:197], v[196:197], 0, s[0:1]
	global_load_dword v110, v[198:199], off
	v_lshl_add_u64 v[198:199], v[198:199], 0, s[0:1]
	global_load_dword v111, v[200:201], off
	v_lshl_add_u64 v[200:201], v[200:201], 0, s[0:1]
	global_load_dword v112, v[194:195], off
	v_lshl_add_u64 v[194:195], v[194:195], 0, s[0:1]
	global_load_dword v113, v[196:197], off
	v_lshl_add_u64 v[196:197], v[196:197], 0, s[0:1]
	global_load_dword v114, v[198:199], off
	v_lshl_add_u64 v[198:199], v[198:199], 0, s[0:1]
	global_load_dword v115, v[200:201], off
	v_lshl_add_u64 v[200:201], v[200:201], 0, s[0:1]
	global_load_dword v116, v[194:195], off
	v_lshl_add_u64 v[194:195], v[194:195], 0, s[0:1]
	global_load_dword v117, v[196:197], off
	v_lshl_add_u64 v[196:197], v[196:197], 0, s[0:1]
	global_load_dword v118, v[198:199], off
	v_lshl_add_u64 v[198:199], v[198:199], 0, s[0:1]
	global_load_dword v119, v[200:201], off
	v_lshl_add_u64 v[200:201], v[200:201], 0, s[0:1]
	global_load_dword v120, v[194:195], off
	v_lshl_add_u64 v[194:195], v[194:195], 0, s[0:1]
	global_load_dword v121, v[196:197], off
	v_lshl_add_u64 v[196:197], v[196:197], 0, s[0:1]
	global_load_dword v122, v[198:199], off
	v_lshl_add_u64 v[198:199], v[198:199], 0, s[0:1]
	global_load_dword v123, v[200:201], off
	v_lshl_add_u64 v[200:201], v[200:201], 0, s[0:1]
	ds_read_b128 v[14:17], v202 offset:0
	ds_read_b128 v[18:21], v202 offset:4096
	ds_read_b128 v[22:25], v202 offset:8192
	ds_read_b128 v[26:29], v202 offset:12288
	ds_read_b128 v[30:33], v202 offset:16384
	ds_read_b128 v[34:37], v202 offset:20480
	ds_read_b128 v[38:41], v202 offset:24576
	ds_read_b128 v[42:45], v202 offset:28672
	ds_read_b128 v[204:207], v202 offset:16
	ds_read_b128 v[208:211], v202 offset:4112
	ds_read_b128 v[212:215], v202 offset:8208
	ds_read_b128 v[216:219], v202 offset:12304
	ds_read_b128 v[220:223], v202 offset:16400
	ds_read_b128 v[224:227], v202 offset:20496
	ds_read_b128 v[228:231], v202 offset:24592
	ds_read_b128 v[232:235], v202 offset:28688
	s_waitcnt vmcnt(56) lgkmcnt(8)
	v_fma_f32 v10, v64, v14, v10
	v_fma_f32 v11, v64, v18, v11
	v_fma_f32 v8, v64, v22, v8
	v_fma_f32 v9, v64, v26, v9
	v_fma_f32 v6, v64, v30, v6
	v_fma_f32 v7, v64, v34, v7
	v_fma_f32 v4, v64, v38, v4
	v_fma_f32 v5, v64, v42, v5
	v_fma_f32 v10, v65, v15, v10
	v_fma_f32 v11, v65, v19, v11
	v_fma_f32 v8, v65, v23, v8
	v_fma_f32 v9, v65, v27, v9
	v_fma_f32 v6, v65, v31, v6
	v_fma_f32 v7, v65, v35, v7
	v_fma_f32 v4, v65, v39, v4
	v_fma_f32 v5, v65, v43, v5
	v_fma_f32 v10, v66, v16, v10
	v_fma_f32 v11, v66, v20, v11
	v_fma_f32 v8, v66, v24, v8
	v_fma_f32 v9, v66, v28, v9
	v_fma_f32 v6, v66, v32, v6
	v_fma_f32 v7, v66, v36, v7
	v_fma_f32 v4, v66, v40, v4
	v_fma_f32 v5, v66, v44, v5
	v_fma_f32 v10, v67, v17, v10
	v_fma_f32 v11, v67, v21, v11
	v_fma_f32 v8, v67, v25, v8
	v_fma_f32 v9, v67, v29, v9
	v_fma_f32 v6, v67, v33, v6
	v_fma_f32 v7, v67, v37, v7
	v_fma_f32 v4, v67, v41, v4
	v_fma_f32 v5, v67, v45, v5
	global_load_dword v124, v[194:195], off
	v_lshl_add_u64 v[194:195], v[194:195], 0, s[0:1]
	global_load_dword v125, v[196:197], off
	v_lshl_add_u64 v[196:197], v[196:197], 0, s[0:1]
	global_load_dword v126, v[198:199], off
	v_lshl_add_u64 v[198:199], v[198:199], 0, s[0:1]
	global_load_dword v127, v[200:201], off
	v_lshl_add_u64 v[200:201], v[200:201], 0, s[0:1]
	ds_read_b128 v[14:17], v202 offset:32
	ds_read_b128 v[18:21], v202 offset:4128
	ds_read_b128 v[22:25], v202 offset:8224
	ds_read_b128 v[26:29], v202 offset:12320
	ds_read_b128 v[30:33], v202 offset:16416
	ds_read_b128 v[34:37], v202 offset:20512
	ds_read_b128 v[38:41], v202 offset:24608
	ds_read_b128 v[42:45], v202 offset:28704
	s_waitcnt vmcnt(56) lgkmcnt(8)
	v_fma_f32 v10, v68, v204, v10
	v_fma_f32 v11, v68, v208, v11
	v_fma_f32 v8, v68, v212, v8
	v_fma_f32 v9, v68, v216, v9
	v_fma_f32 v6, v68, v220, v6
	v_fma_f32 v7, v68, v224, v7
	v_fma_f32 v4, v68, v228, v4
	v_fma_f32 v5, v68, v232, v5
	v_fma_f32 v10, v69, v205, v10
	v_fma_f32 v11, v69, v209, v11
	v_fma_f32 v8, v69, v213, v8
	v_fma_f32 v9, v69, v217, v9
	v_fma_f32 v6, v69, v221, v6
	v_fma_f32 v7, v69, v225, v7
	v_fma_f32 v4, v69, v229, v4
	v_fma_f32 v5, v69, v233, v5
	v_fma_f32 v10, v70, v206, v10
	v_fma_f32 v11, v70, v210, v11
	v_fma_f32 v8, v70, v214, v8
	v_fma_f32 v9, v70, v218, v9
	v_fma_f32 v6, v70, v222, v6
	v_fma_f32 v7, v70, v226, v7
	v_fma_f32 v4, v70, v230, v4
	v_fma_f32 v5, v70, v234, v5
	v_fma_f32 v10, v71, v207, v10
	v_fma_f32 v11, v71, v211, v11
	v_fma_f32 v8, v71, v215, v8
	v_fma_f32 v9, v71, v219, v9
	v_fma_f32 v6, v71, v223, v6
	v_fma_f32 v7, v71, v227, v7
	v_fma_f32 v4, v71, v231, v4
	v_fma_f32 v5, v71, v235, v5
	global_load_dword v128, v[194:195], off
	v_lshl_add_u64 v[194:195], v[194:195], 0, s[0:1]
	global_load_dword v129, v[196:197], off
	v_lshl_add_u64 v[196:197], v[196:197], 0, s[0:1]
	global_load_dword v130, v[198:199], off
	v_lshl_add_u64 v[198:199], v[198:199], 0, s[0:1]
	global_load_dword v131, v[200:201], off
	v_lshl_add_u64 v[200:201], v[200:201], 0, s[0:1]
	ds_read_b128 v[204:207], v202 offset:48
	ds_read_b128 v[208:211], v202 offset:4144
	ds_read_b128 v[212:215], v202 offset:8240
	ds_read_b128 v[216:219], v202 offset:12336
	ds_read_b128 v[220:223], v202 offset:16432
	ds_read_b128 v[224:227], v202 offset:20528
	ds_read_b128 v[228:231], v202 offset:24624
	ds_read_b128 v[232:235], v202 offset:28720
	s_waitcnt vmcnt(56) lgkmcnt(8)
	v_fma_f32 v10, v72, v14, v10
	v_fma_f32 v11, v72, v18, v11
	v_fma_f32 v8, v72, v22, v8
	v_fma_f32 v9, v72, v26, v9
	v_fma_f32 v6, v72, v30, v6
	v_fma_f32 v7, v72, v34, v7
	v_fma_f32 v4, v72, v38, v4
	v_fma_f32 v5, v72, v42, v5
	v_fma_f32 v10, v73, v15, v10
	v_fma_f32 v11, v73, v19, v11
	v_fma_f32 v8, v73, v23, v8
	v_fma_f32 v9, v73, v27, v9
	v_fma_f32 v6, v73, v31, v6
	v_fma_f32 v7, v73, v35, v7
	v_fma_f32 v4, v73, v39, v4
	v_fma_f32 v5, v73, v43, v5
	v_fma_f32 v10, v74, v16, v10
	v_fma_f32 v11, v74, v20, v11
	v_fma_f32 v8, v74, v24, v8
	v_fma_f32 v9, v74, v28, v9
	v_fma_f32 v6, v74, v32, v6
	v_fma_f32 v7, v74, v36, v7
	v_fma_f32 v4, v74, v40, v4
	v_fma_f32 v5, v74, v44, v5
	v_fma_f32 v10, v75, v17, v10
	v_fma_f32 v11, v75, v21, v11
	v_fma_f32 v8, v75, v25, v8
	v_fma_f32 v9, v75, v29, v9
	v_fma_f32 v6, v75, v33, v6
	v_fma_f32 v7, v75, v37, v7
	v_fma_f32 v4, v75, v41, v4
	v_fma_f32 v5, v75, v45, v5
	global_load_dword v132, v[194:195], off
	v_lshl_add_u64 v[194:195], v[194:195], 0, s[0:1]
	global_load_dword v133, v[196:197], off
	v_lshl_add_u64 v[196:197], v[196:197], 0, s[0:1]
	global_load_dword v134, v[198:199], off
	v_lshl_add_u64 v[198:199], v[198:199], 0, s[0:1]
	global_load_dword v135, v[200:201], off
	v_lshl_add_u64 v[200:201], v[200:201], 0, s[0:1]
	ds_read_b128 v[14:17], v202 offset:64
	ds_read_b128 v[18:21], v202 offset:4160
	ds_read_b128 v[22:25], v202 offset:8256
	ds_read_b128 v[26:29], v202 offset:12352
	ds_read_b128 v[30:33], v202 offset:16448
	ds_read_b128 v[34:37], v202 offset:20544
	ds_read_b128 v[38:41], v202 offset:24640
	ds_read_b128 v[42:45], v202 offset:28736
	s_waitcnt vmcnt(56) lgkmcnt(8)
	v_fma_f32 v10, v76, v204, v10
	v_fma_f32 v11, v76, v208, v11
	v_fma_f32 v8, v76, v212, v8
	v_fma_f32 v9, v76, v216, v9
	v_fma_f32 v6, v76, v220, v6
	v_fma_f32 v7, v76, v224, v7
	v_fma_f32 v4, v76, v228, v4
	v_fma_f32 v5, v76, v232, v5
	v_fma_f32 v10, v77, v205, v10
	v_fma_f32 v11, v77, v209, v11
	v_fma_f32 v8, v77, v213, v8
	v_fma_f32 v9, v77, v217, v9
	v_fma_f32 v6, v77, v221, v6
	v_fma_f32 v7, v77, v225, v7
	v_fma_f32 v4, v77, v229, v4
	v_fma_f32 v5, v77, v233, v5
	v_fma_f32 v10, v78, v206, v10
	v_fma_f32 v11, v78, v210, v11
	v_fma_f32 v8, v78, v214, v8
	v_fma_f32 v9, v78, v218, v9
	v_fma_f32 v6, v78, v222, v6
	v_fma_f32 v7, v78, v226, v7
	v_fma_f32 v4, v78, v230, v4
	v_fma_f32 v5, v78, v234, v5
	v_fma_f32 v10, v79, v207, v10
	v_fma_f32 v11, v79, v211, v11
	v_fma_f32 v8, v79, v215, v8
	v_fma_f32 v9, v79, v219, v9
	v_fma_f32 v6, v79, v223, v6
	v_fma_f32 v7, v79, v227, v7
	v_fma_f32 v4, v79, v231, v4
	v_fma_f32 v5, v79, v235, v5
	global_load_dword v136, v[194:195], off
	v_lshl_add_u64 v[194:195], v[194:195], 0, s[0:1]
	global_load_dword v137, v[196:197], off
	v_lshl_add_u64 v[196:197], v[196:197], 0, s[0:1]
	global_load_dword v138, v[198:199], off
	v_lshl_add_u64 v[198:199], v[198:199], 0, s[0:1]
	global_load_dword v139, v[200:201], off
	v_lshl_add_u64 v[200:201], v[200:201], 0, s[0:1]
	ds_read_b128 v[204:207], v202 offset:80
	ds_read_b128 v[208:211], v202 offset:4176
	ds_read_b128 v[212:215], v202 offset:8272
	ds_read_b128 v[216:219], v202 offset:12368
	ds_read_b128 v[220:223], v202 offset:16464
	ds_read_b128 v[224:227], v202 offset:20560
	ds_read_b128 v[228:231], v202 offset:24656
	ds_read_b128 v[232:235], v202 offset:28752
	s_waitcnt vmcnt(56) lgkmcnt(8)
	v_fma_f32 v10, v80, v14, v10
	v_fma_f32 v11, v80, v18, v11
	v_fma_f32 v8, v80, v22, v8
	v_fma_f32 v9, v80, v26, v9
	v_fma_f32 v6, v80, v30, v6
	v_fma_f32 v7, v80, v34, v7
	v_fma_f32 v4, v80, v38, v4
	v_fma_f32 v5, v80, v42, v5
	v_fma_f32 v10, v81, v15, v10
	v_fma_f32 v11, v81, v19, v11
	v_fma_f32 v8, v81, v23, v8
	v_fma_f32 v9, v81, v27, v9
	v_fma_f32 v6, v81, v31, v6
	v_fma_f32 v7, v81, v35, v7
	v_fma_f32 v4, v81, v39, v4
	v_fma_f32 v5, v81, v43, v5
	v_fma_f32 v10, v82, v16, v10
	v_fma_f32 v11, v82, v20, v11
	v_fma_f32 v8, v82, v24, v8
	v_fma_f32 v9, v82, v28, v9
	v_fma_f32 v6, v82, v32, v6
	v_fma_f32 v7, v82, v36, v7
	v_fma_f32 v4, v82, v40, v4
	v_fma_f32 v5, v82, v44, v5
	v_fma_f32 v10, v83, v17, v10
	v_fma_f32 v11, v83, v21, v11
	v_fma_f32 v8, v83, v25, v8
	v_fma_f32 v9, v83, v29, v9
	v_fma_f32 v6, v83, v33, v6
	v_fma_f32 v7, v83, v37, v7
	v_fma_f32 v4, v83, v41, v4
	v_fma_f32 v5, v83, v45, v5
	global_load_dword v140, v[194:195], off
	v_lshl_add_u64 v[194:195], v[194:195], 0, s[0:1]
	global_load_dword v141, v[196:197], off
	v_lshl_add_u64 v[196:197], v[196:197], 0, s[0:1]
	global_load_dword v142, v[198:199], off
	v_lshl_add_u64 v[198:199], v[198:199], 0, s[0:1]
	global_load_dword v143, v[200:201], off
	v_lshl_add_u64 v[200:201], v[200:201], 0, s[0:1]
	ds_read_b128 v[14:17], v202 offset:96
	ds_read_b128 v[18:21], v202 offset:4192
	ds_read_b128 v[22:25], v202 offset:8288
	ds_read_b128 v[26:29], v202 offset:12384
	ds_read_b128 v[30:33], v202 offset:16480
	ds_read_b128 v[34:37], v202 offset:20576
	ds_read_b128 v[38:41], v202 offset:24672
	ds_read_b128 v[42:45], v202 offset:28768
	s_waitcnt vmcnt(56) lgkmcnt(8)
	v_fma_f32 v10, v84, v204, v10
	v_fma_f32 v11, v84, v208, v11
	v_fma_f32 v8, v84, v212, v8
	v_fma_f32 v9, v84, v216, v9
	v_fma_f32 v6, v84, v220, v6
	v_fma_f32 v7, v84, v224, v7
	v_fma_f32 v4, v84, v228, v4
	v_fma_f32 v5, v84, v232, v5
	v_fma_f32 v10, v85, v205, v10
	v_fma_f32 v11, v85, v209, v11
	v_fma_f32 v8, v85, v213, v8
	v_fma_f32 v9, v85, v217, v9
	v_fma_f32 v6, v85, v221, v6
	v_fma_f32 v7, v85, v225, v7
	v_fma_f32 v4, v85, v229, v4
	v_fma_f32 v5, v85, v233, v5
	v_fma_f32 v10, v86, v206, v10
	v_fma_f32 v11, v86, v210, v11
	v_fma_f32 v8, v86, v214, v8
	v_fma_f32 v9, v86, v218, v9
	v_fma_f32 v6, v86, v222, v6
	v_fma_f32 v7, v86, v226, v7
	v_fma_f32 v4, v86, v230, v4
	v_fma_f32 v5, v86, v234, v5
	v_fma_f32 v10, v87, v207, v10
	v_fma_f32 v11, v87, v211, v11
	v_fma_f32 v8, v87, v215, v8
	v_fma_f32 v9, v87, v219, v9
	v_fma_f32 v6, v87, v223, v6
	v_fma_f32 v7, v87, v227, v7
	v_fma_f32 v4, v87, v231, v4
	v_fma_f32 v5, v87, v235, v5
	global_load_dword v144, v[194:195], off
	v_lshl_add_u64 v[194:195], v[194:195], 0, s[0:1]
	global_load_dword v145, v[196:197], off
	v_lshl_add_u64 v[196:197], v[196:197], 0, s[0:1]
	global_load_dword v146, v[198:199], off
	v_lshl_add_u64 v[198:199], v[198:199], 0, s[0:1]
	global_load_dword v147, v[200:201], off
	v_lshl_add_u64 v[200:201], v[200:201], 0, s[0:1]
	ds_read_b128 v[204:207], v202 offset:112
	ds_read_b128 v[208:211], v202 offset:4208
	ds_read_b128 v[212:215], v202 offset:8304
	ds_read_b128 v[216:219], v202 offset:12400
	ds_read_b128 v[220:223], v202 offset:16496
	ds_read_b128 v[224:227], v202 offset:20592
	ds_read_b128 v[228:231], v202 offset:24688
	ds_read_b128 v[232:235], v202 offset:28784
	s_waitcnt vmcnt(56) lgkmcnt(8)
	v_fma_f32 v10, v88, v14, v10
	v_fma_f32 v11, v88, v18, v11
	v_fma_f32 v8, v88, v22, v8
	v_fma_f32 v9, v88, v26, v9
	v_fma_f32 v6, v88, v30, v6
	v_fma_f32 v7, v88, v34, v7
	v_fma_f32 v4, v88, v38, v4
	v_fma_f32 v5, v88, v42, v5
	v_fma_f32 v10, v89, v15, v10
	v_fma_f32 v11, v89, v19, v11
	v_fma_f32 v8, v89, v23, v8
	v_fma_f32 v9, v89, v27, v9
	v_fma_f32 v6, v89, v31, v6
	v_fma_f32 v7, v89, v35, v7
	v_fma_f32 v4, v89, v39, v4
	v_fma_f32 v5, v89, v43, v5
	v_fma_f32 v10, v90, v16, v10
	v_fma_f32 v11, v90, v20, v11
	v_fma_f32 v8, v90, v24, v8
	v_fma_f32 v9, v90, v28, v9
	v_fma_f32 v6, v90, v32, v6
	v_fma_f32 v7, v90, v36, v7
	v_fma_f32 v4, v90, v40, v4
	v_fma_f32 v5, v90, v44, v5
	v_fma_f32 v10, v91, v17, v10
	v_fma_f32 v11, v91, v21, v11
	v_fma_f32 v8, v91, v25, v8
	v_fma_f32 v9, v91, v29, v9
	v_fma_f32 v6, v91, v33, v6
	v_fma_f32 v7, v91, v37, v7
	v_fma_f32 v4, v91, v41, v4
	v_fma_f32 v5, v91, v45, v5
	global_load_dword v148, v[194:195], off
	v_lshl_add_u64 v[194:195], v[194:195], 0, s[0:1]
	global_load_dword v149, v[196:197], off
	v_lshl_add_u64 v[196:197], v[196:197], 0, s[0:1]
	global_load_dword v150, v[198:199], off
	v_lshl_add_u64 v[198:199], v[198:199], 0, s[0:1]
	global_load_dword v151, v[200:201], off
	v_lshl_add_u64 v[200:201], v[200:201], 0, s[0:1]
	ds_read_b128 v[14:17], v202 offset:128
	ds_read_b128 v[18:21], v202 offset:4224
	ds_read_b128 v[22:25], v202 offset:8320
	ds_read_b128 v[26:29], v202 offset:12416
	ds_read_b128 v[30:33], v202 offset:16512
	ds_read_b128 v[34:37], v202 offset:20608
	ds_read_b128 v[38:41], v202 offset:24704
	ds_read_b128 v[42:45], v202 offset:28800
	s_waitcnt vmcnt(56) lgkmcnt(8)
	v_fma_f32 v10, v92, v204, v10
	v_fma_f32 v11, v92, v208, v11
	v_fma_f32 v8, v92, v212, v8
	v_fma_f32 v9, v92, v216, v9
	v_fma_f32 v6, v92, v220, v6
	v_fma_f32 v7, v92, v224, v7
	v_fma_f32 v4, v92, v228, v4
	v_fma_f32 v5, v92, v232, v5
	v_fma_f32 v10, v93, v205, v10
	v_fma_f32 v11, v93, v209, v11
	v_fma_f32 v8, v93, v213, v8
	v_fma_f32 v9, v93, v217, v9
	v_fma_f32 v6, v93, v221, v6
	v_fma_f32 v7, v93, v225, v7
	v_fma_f32 v4, v93, v229, v4
	v_fma_f32 v5, v93, v233, v5
	v_fma_f32 v10, v94, v206, v10
	v_fma_f32 v11, v94, v210, v11
	v_fma_f32 v8, v94, v214, v8
	v_fma_f32 v9, v94, v218, v9
	v_fma_f32 v6, v94, v222, v6
	v_fma_f32 v7, v94, v226, v7
	v_fma_f32 v4, v94, v230, v4
	v_fma_f32 v5, v94, v234, v5
	v_fma_f32 v10, v95, v207, v10
	v_fma_f32 v11, v95, v211, v11
	v_fma_f32 v8, v95, v215, v8
	v_fma_f32 v9, v95, v219, v9
	v_fma_f32 v6, v95, v223, v6
	v_fma_f32 v7, v95, v227, v7
	v_fma_f32 v4, v95, v231, v4
	v_fma_f32 v5, v95, v235, v5
	global_load_dword v152, v[194:195], off
	v_lshl_add_u64 v[194:195], v[194:195], 0, s[0:1]
	global_load_dword v153, v[196:197], off
	v_lshl_add_u64 v[196:197], v[196:197], 0, s[0:1]
	global_load_dword v154, v[198:199], off
	v_lshl_add_u64 v[198:199], v[198:199], 0, s[0:1]
	global_load_dword v155, v[200:201], off
	v_lshl_add_u64 v[200:201], v[200:201], 0, s[0:1]
	ds_read_b128 v[204:207], v202 offset:144
	ds_read_b128 v[208:211], v202 offset:4240
	ds_read_b128 v[212:215], v202 offset:8336
	ds_read_b128 v[216:219], v202 offset:12432
	ds_read_b128 v[220:223], v202 offset:16528
	ds_read_b128 v[224:227], v202 offset:20624
	ds_read_b128 v[228:231], v202 offset:24720
	ds_read_b128 v[232:235], v202 offset:28816
	s_waitcnt vmcnt(56) lgkmcnt(8)
	v_fma_f32 v10, v96, v14, v10
	v_fma_f32 v11, v96, v18, v11
	v_fma_f32 v8, v96, v22, v8
	v_fma_f32 v9, v96, v26, v9
	v_fma_f32 v6, v96, v30, v6
	v_fma_f32 v7, v96, v34, v7
	v_fma_f32 v4, v96, v38, v4
	v_fma_f32 v5, v96, v42, v5
	v_fma_f32 v10, v97, v15, v10
	v_fma_f32 v11, v97, v19, v11
	v_fma_f32 v8, v97, v23, v8
	v_fma_f32 v9, v97, v27, v9
	v_fma_f32 v6, v97, v31, v6
	v_fma_f32 v7, v97, v35, v7
	v_fma_f32 v4, v97, v39, v4
	v_fma_f32 v5, v97, v43, v5
	v_fma_f32 v10, v98, v16, v10
	v_fma_f32 v11, v98, v20, v11
	v_fma_f32 v8, v98, v24, v8
	v_fma_f32 v9, v98, v28, v9
	v_fma_f32 v6, v98, v32, v6
	v_fma_f32 v7, v98, v36, v7
	v_fma_f32 v4, v98, v40, v4
	v_fma_f32 v5, v98, v44, v5
	v_fma_f32 v10, v99, v17, v10
	v_fma_f32 v11, v99, v21, v11
	v_fma_f32 v8, v99, v25, v8
	v_fma_f32 v9, v99, v29, v9
	v_fma_f32 v6, v99, v33, v6
	v_fma_f32 v7, v99, v37, v7
	v_fma_f32 v4, v99, v41, v4
	v_fma_f32 v5, v99, v45, v5
	global_load_dword v156, v[194:195], off
	v_lshl_add_u64 v[194:195], v[194:195], 0, s[0:1]
	global_load_dword v157, v[196:197], off
	v_lshl_add_u64 v[196:197], v[196:197], 0, s[0:1]
	global_load_dword v158, v[198:199], off
	v_lshl_add_u64 v[198:199], v[198:199], 0, s[0:1]
	global_load_dword v159, v[200:201], off
	v_lshl_add_u64 v[200:201], v[200:201], 0, s[0:1]
	ds_read_b128 v[14:17], v202 offset:160
	ds_read_b128 v[18:21], v202 offset:4256
	ds_read_b128 v[22:25], v202 offset:8352
	ds_read_b128 v[26:29], v202 offset:12448
	ds_read_b128 v[30:33], v202 offset:16544
	ds_read_b128 v[34:37], v202 offset:20640
	ds_read_b128 v[38:41], v202 offset:24736
	ds_read_b128 v[42:45], v202 offset:28832
	s_waitcnt vmcnt(56) lgkmcnt(8)
	v_fma_f32 v10, v100, v204, v10
	v_fma_f32 v11, v100, v208, v11
	v_fma_f32 v8, v100, v212, v8
	v_fma_f32 v9, v100, v216, v9
	v_fma_f32 v6, v100, v220, v6
	v_fma_f32 v7, v100, v224, v7
	v_fma_f32 v4, v100, v228, v4
	v_fma_f32 v5, v100, v232, v5
	v_fma_f32 v10, v101, v205, v10
	v_fma_f32 v11, v101, v209, v11
	v_fma_f32 v8, v101, v213, v8
	v_fma_f32 v9, v101, v217, v9
	v_fma_f32 v6, v101, v221, v6
	v_fma_f32 v7, v101, v225, v7
	v_fma_f32 v4, v101, v229, v4
	v_fma_f32 v5, v101, v233, v5
	v_fma_f32 v10, v102, v206, v10
	v_fma_f32 v11, v102, v210, v11
	v_fma_f32 v8, v102, v214, v8
	v_fma_f32 v9, v102, v218, v9
	v_fma_f32 v6, v102, v222, v6
	v_fma_f32 v7, v102, v226, v7
	v_fma_f32 v4, v102, v230, v4
	v_fma_f32 v5, v102, v234, v5
	v_fma_f32 v10, v103, v207, v10
	v_fma_f32 v11, v103, v211, v11
	v_fma_f32 v8, v103, v215, v8
	v_fma_f32 v9, v103, v219, v9
	v_fma_f32 v6, v103, v223, v6
	v_fma_f32 v7, v103, v227, v7
	v_fma_f32 v4, v103, v231, v4
	v_fma_f32 v5, v103, v235, v5
	global_load_dword v160, v[194:195], off
	v_lshl_add_u64 v[194:195], v[194:195], 0, s[0:1]
	global_load_dword v161, v[196:197], off
	v_lshl_add_u64 v[196:197], v[196:197], 0, s[0:1]
	global_load_dword v162, v[198:199], off
	v_lshl_add_u64 v[198:199], v[198:199], 0, s[0:1]
	global_load_dword v163, v[200:201], off
	v_lshl_add_u64 v[200:201], v[200:201], 0, s[0:1]
	ds_read_b128 v[204:207], v202 offset:176
	ds_read_b128 v[208:211], v202 offset:4272
	ds_read_b128 v[212:215], v202 offset:8368
	ds_read_b128 v[216:219], v202 offset:12464
	ds_read_b128 v[220:223], v202 offset:16560
	ds_read_b128 v[224:227], v202 offset:20656
	ds_read_b128 v[228:231], v202 offset:24752
	ds_read_b128 v[232:235], v202 offset:28848
	s_waitcnt vmcnt(56) lgkmcnt(8)
	v_fma_f32 v10, v104, v14, v10
	v_fma_f32 v11, v104, v18, v11
	v_fma_f32 v8, v104, v22, v8
	v_fma_f32 v9, v104, v26, v9
	v_fma_f32 v6, v104, v30, v6
	v_fma_f32 v7, v104, v34, v7
	v_fma_f32 v4, v104, v38, v4
	v_fma_f32 v5, v104, v42, v5
	v_fma_f32 v10, v105, v15, v10
	v_fma_f32 v11, v105, v19, v11
	v_fma_f32 v8, v105, v23, v8
	v_fma_f32 v9, v105, v27, v9
	v_fma_f32 v6, v105, v31, v6
	v_fma_f32 v7, v105, v35, v7
	v_fma_f32 v4, v105, v39, v4
	v_fma_f32 v5, v105, v43, v5
	v_fma_f32 v10, v106, v16, v10
	v_fma_f32 v11, v106, v20, v11
	v_fma_f32 v8, v106, v24, v8
	v_fma_f32 v9, v106, v28, v9
	v_fma_f32 v6, v106, v32, v6
	v_fma_f32 v7, v106, v36, v7
	v_fma_f32 v4, v106, v40, v4
	v_fma_f32 v5, v106, v44, v5
	v_fma_f32 v10, v107, v17, v10
	v_fma_f32 v11, v107, v21, v11
	v_fma_f32 v8, v107, v25, v8
	v_fma_f32 v9, v107, v29, v9
	v_fma_f32 v6, v107, v33, v6
	v_fma_f32 v7, v107, v37, v7
	v_fma_f32 v4, v107, v41, v4
	v_fma_f32 v5, v107, v45, v5
	global_load_dword v164, v[194:195], off
	v_lshl_add_u64 v[194:195], v[194:195], 0, s[0:1]
	global_load_dword v165, v[196:197], off
	v_lshl_add_u64 v[196:197], v[196:197], 0, s[0:1]
	global_load_dword v166, v[198:199], off
	v_lshl_add_u64 v[198:199], v[198:199], 0, s[0:1]
	global_load_dword v167, v[200:201], off
	v_lshl_add_u64 v[200:201], v[200:201], 0, s[0:1]
	ds_read_b128 v[14:17], v202 offset:192
	ds_read_b128 v[18:21], v202 offset:4288
	ds_read_b128 v[22:25], v202 offset:8384
	ds_read_b128 v[26:29], v202 offset:12480
	ds_read_b128 v[30:33], v202 offset:16576
	ds_read_b128 v[34:37], v202 offset:20672
	ds_read_b128 v[38:41], v202 offset:24768
	ds_read_b128 v[42:45], v202 offset:28864
	s_waitcnt vmcnt(56) lgkmcnt(8)
	v_fma_f32 v10, v108, v204, v10
	v_fma_f32 v11, v108, v208, v11
	v_fma_f32 v8, v108, v212, v8
	v_fma_f32 v9, v108, v216, v9
	v_fma_f32 v6, v108, v220, v6
	v_fma_f32 v7, v108, v224, v7
	v_fma_f32 v4, v108, v228, v4
	v_fma_f32 v5, v108, v232, v5
	v_fma_f32 v10, v109, v205, v10
	v_fma_f32 v11, v109, v209, v11
	v_fma_f32 v8, v109, v213, v8
	v_fma_f32 v9, v109, v217, v9
	v_fma_f32 v6, v109, v221, v6
	v_fma_f32 v7, v109, v225, v7
	v_fma_f32 v4, v109, v229, v4
	v_fma_f32 v5, v109, v233, v5
	v_fma_f32 v10, v110, v206, v10
	v_fma_f32 v11, v110, v210, v11
	v_fma_f32 v8, v110, v214, v8
	v_fma_f32 v9, v110, v218, v9
	v_fma_f32 v6, v110, v222, v6
	v_fma_f32 v7, v110, v226, v7
	v_fma_f32 v4, v110, v230, v4
	v_fma_f32 v5, v110, v234, v5
	v_fma_f32 v10, v111, v207, v10
	v_fma_f32 v11, v111, v211, v11
	v_fma_f32 v8, v111, v215, v8
	v_fma_f32 v9, v111, v219, v9
	v_fma_f32 v6, v111, v223, v6
	v_fma_f32 v7, v111, v227, v7
	v_fma_f32 v4, v111, v231, v4
	v_fma_f32 v5, v111, v235, v5
	global_load_dword v168, v[194:195], off
	v_lshl_add_u64 v[194:195], v[194:195], 0, s[0:1]
	global_load_dword v169, v[196:197], off
	v_lshl_add_u64 v[196:197], v[196:197], 0, s[0:1]
	global_load_dword v170, v[198:199], off
	v_lshl_add_u64 v[198:199], v[198:199], 0, s[0:1]
	global_load_dword v171, v[200:201], off
	v_lshl_add_u64 v[200:201], v[200:201], 0, s[0:1]
	ds_read_b128 v[204:207], v202 offset:208
	ds_read_b128 v[208:211], v202 offset:4304
	ds_read_b128 v[212:215], v202 offset:8400
	ds_read_b128 v[216:219], v202 offset:12496
	ds_read_b128 v[220:223], v202 offset:16592
	ds_read_b128 v[224:227], v202 offset:20688
	ds_read_b128 v[228:231], v202 offset:24784
	ds_read_b128 v[232:235], v202 offset:28880
	s_waitcnt vmcnt(56) lgkmcnt(8)
	v_fma_f32 v10, v112, v14, v10
	v_fma_f32 v11, v112, v18, v11
	v_fma_f32 v8, v112, v22, v8
	v_fma_f32 v9, v112, v26, v9
	v_fma_f32 v6, v112, v30, v6
	v_fma_f32 v7, v112, v34, v7
	v_fma_f32 v4, v112, v38, v4
	v_fma_f32 v5, v112, v42, v5
	v_fma_f32 v10, v113, v15, v10
	v_fma_f32 v11, v113, v19, v11
	v_fma_f32 v8, v113, v23, v8
	v_fma_f32 v9, v113, v27, v9
	v_fma_f32 v6, v113, v31, v6
	v_fma_f32 v7, v113, v35, v7
	v_fma_f32 v4, v113, v39, v4
	v_fma_f32 v5, v113, v43, v5
	v_fma_f32 v10, v114, v16, v10
	v_fma_f32 v11, v114, v20, v11
	v_fma_f32 v8, v114, v24, v8
	v_fma_f32 v9, v114, v28, v9
	v_fma_f32 v6, v114, v32, v6
	v_fma_f32 v7, v114, v36, v7
	v_fma_f32 v4, v114, v40, v4
	v_fma_f32 v5, v114, v44, v5
	v_fma_f32 v10, v115, v17, v10
	v_fma_f32 v11, v115, v21, v11
	v_fma_f32 v8, v115, v25, v8
	v_fma_f32 v9, v115, v29, v9
	v_fma_f32 v6, v115, v33, v6
	v_fma_f32 v7, v115, v37, v7
	v_fma_f32 v4, v115, v41, v4
	v_fma_f32 v5, v115, v45, v5
	global_load_dword v172, v[194:195], off
	v_lshl_add_u64 v[194:195], v[194:195], 0, s[0:1]
	global_load_dword v173, v[196:197], off
	v_lshl_add_u64 v[196:197], v[196:197], 0, s[0:1]
	global_load_dword v174, v[198:199], off
	v_lshl_add_u64 v[198:199], v[198:199], 0, s[0:1]
	global_load_dword v175, v[200:201], off
	v_lshl_add_u64 v[200:201], v[200:201], 0, s[0:1]
	ds_read_b128 v[14:17], v202 offset:224
	ds_read_b128 v[18:21], v202 offset:4320
	ds_read_b128 v[22:25], v202 offset:8416
	ds_read_b128 v[26:29], v202 offset:12512
	ds_read_b128 v[30:33], v202 offset:16608
	ds_read_b128 v[34:37], v202 offset:20704
	ds_read_b128 v[38:41], v202 offset:24800
	ds_read_b128 v[42:45], v202 offset:28896
	s_waitcnt vmcnt(56) lgkmcnt(8)
	v_fma_f32 v10, v116, v204, v10
	v_fma_f32 v11, v116, v208, v11
	v_fma_f32 v8, v116, v212, v8
	v_fma_f32 v9, v116, v216, v9
	v_fma_f32 v6, v116, v220, v6
	v_fma_f32 v7, v116, v224, v7
	v_fma_f32 v4, v116, v228, v4
	v_fma_f32 v5, v116, v232, v5
	v_fma_f32 v10, v117, v205, v10
	v_fma_f32 v11, v117, v209, v11
	v_fma_f32 v8, v117, v213, v8
	v_fma_f32 v9, v117, v217, v9
	v_fma_f32 v6, v117, v221, v6
	v_fma_f32 v7, v117, v225, v7
	v_fma_f32 v4, v117, v229, v4
	v_fma_f32 v5, v117, v233, v5
	v_fma_f32 v10, v118, v206, v10
	v_fma_f32 v11, v118, v210, v11
	v_fma_f32 v8, v118, v214, v8
	v_fma_f32 v9, v118, v218, v9
	v_fma_f32 v6, v118, v222, v6
	v_fma_f32 v7, v118, v226, v7
	v_fma_f32 v4, v118, v230, v4
	v_fma_f32 v5, v118, v234, v5
	v_fma_f32 v10, v119, v207, v10
	v_fma_f32 v11, v119, v211, v11
	v_fma_f32 v8, v119, v215, v8
	v_fma_f32 v9, v119, v219, v9
	v_fma_f32 v6, v119, v223, v6
	v_fma_f32 v7, v119, v227, v7
	v_fma_f32 v4, v119, v231, v4
	v_fma_f32 v5, v119, v235, v5
	global_load_dword v176, v[194:195], off
	v_lshl_add_u64 v[194:195], v[194:195], 0, s[0:1]
	global_load_dword v177, v[196:197], off
	v_lshl_add_u64 v[196:197], v[196:197], 0, s[0:1]
	global_load_dword v178, v[198:199], off
	v_lshl_add_u64 v[198:199], v[198:199], 0, s[0:1]
	global_load_dword v180, v[200:201], off
	v_lshl_add_u64 v[200:201], v[200:201], 0, s[0:1]
	ds_read_b128 v[204:207], v202 offset:240
	ds_read_b128 v[208:211], v202 offset:4336
	ds_read_b128 v[212:215], v202 offset:8432
	ds_read_b128 v[216:219], v202 offset:12528
	ds_read_b128 v[220:223], v202 offset:16624
	ds_read_b128 v[224:227], v202 offset:20720
	ds_read_b128 v[228:231], v202 offset:24816
	ds_read_b128 v[232:235], v202 offset:28912
	s_waitcnt vmcnt(56) lgkmcnt(8)
	v_fma_f32 v10, v120, v14, v10
	v_fma_f32 v11, v120, v18, v11
	v_fma_f32 v8, v120, v22, v8
	v_fma_f32 v9, v120, v26, v9
	v_fma_f32 v6, v120, v30, v6
	v_fma_f32 v7, v120, v34, v7
	v_fma_f32 v4, v120, v38, v4
	v_fma_f32 v5, v120, v42, v5
	v_fma_f32 v10, v121, v15, v10
	v_fma_f32 v11, v121, v19, v11
	v_fma_f32 v8, v121, v23, v8
	v_fma_f32 v9, v121, v27, v9
	v_fma_f32 v6, v121, v31, v6
	v_fma_f32 v7, v121, v35, v7
	v_fma_f32 v4, v121, v39, v4
	v_fma_f32 v5, v121, v43, v5
	v_fma_f32 v10, v122, v16, v10
	v_fma_f32 v11, v122, v20, v11
	v_fma_f32 v8, v122, v24, v8
	v_fma_f32 v9, v122, v28, v9
	v_fma_f32 v6, v122, v32, v6
	v_fma_f32 v7, v122, v36, v7
	v_fma_f32 v4, v122, v40, v4
	v_fma_f32 v5, v122, v44, v5
	v_fma_f32 v10, v123, v17, v10
	v_fma_f32 v11, v123, v21, v11
	v_fma_f32 v8, v123, v25, v8
	v_fma_f32 v9, v123, v29, v9
	v_fma_f32 v6, v123, v33, v6
	v_fma_f32 v7, v123, v37, v7
	v_fma_f32 v4, v123, v41, v4
	v_fma_f32 v5, v123, v45, v5
	global_load_dword v181, v[194:195], off
	v_lshl_add_u64 v[194:195], v[194:195], 0, s[0:1]
	global_load_dword v182, v[196:197], off
	v_lshl_add_u64 v[196:197], v[196:197], 0, s[0:1]
	global_load_dword v183, v[198:199], off
	v_lshl_add_u64 v[198:199], v[198:199], 0, s[0:1]
	global_load_dword v184, v[200:201], off
	v_lshl_add_u64 v[200:201], v[200:201], 0, s[0:1]
	ds_read_b128 v[14:17], v202 offset:256
	ds_read_b128 v[18:21], v202 offset:4352
	ds_read_b128 v[22:25], v202 offset:8448
	ds_read_b128 v[26:29], v202 offset:12544
	ds_read_b128 v[30:33], v202 offset:16640
	ds_read_b128 v[34:37], v202 offset:20736
	ds_read_b128 v[38:41], v202 offset:24832
	ds_read_b128 v[42:45], v202 offset:28928
	s_waitcnt vmcnt(56) lgkmcnt(8)
	v_fma_f32 v10, v124, v204, v10
	v_fma_f32 v11, v124, v208, v11
	v_fma_f32 v8, v124, v212, v8
	v_fma_f32 v9, v124, v216, v9
	v_fma_f32 v6, v124, v220, v6
	v_fma_f32 v7, v124, v224, v7
	v_fma_f32 v4, v124, v228, v4
	v_fma_f32 v5, v124, v232, v5
	v_fma_f32 v10, v125, v205, v10
	v_fma_f32 v11, v125, v209, v11
	v_fma_f32 v8, v125, v213, v8
	v_fma_f32 v9, v125, v217, v9
	v_fma_f32 v6, v125, v221, v6
	v_fma_f32 v7, v125, v225, v7
	v_fma_f32 v4, v125, v229, v4
	v_fma_f32 v5, v125, v233, v5
	v_fma_f32 v10, v126, v206, v10
	v_fma_f32 v11, v126, v210, v11
	v_fma_f32 v8, v126, v214, v8
	v_fma_f32 v9, v126, v218, v9
	v_fma_f32 v6, v126, v222, v6
	v_fma_f32 v7, v126, v226, v7
	v_fma_f32 v4, v126, v230, v4
	v_fma_f32 v5, v126, v234, v5
	v_fma_f32 v10, v127, v207, v10
	v_fma_f32 v11, v127, v211, v11
	v_fma_f32 v8, v127, v215, v8
	v_fma_f32 v9, v127, v219, v9
	v_fma_f32 v6, v127, v223, v6
	v_fma_f32 v7, v127, v227, v7
	v_fma_f32 v4, v127, v231, v4
	v_fma_f32 v5, v127, v235, v5
	global_load_dword v185, v[194:195], off
	v_lshl_add_u64 v[194:195], v[194:195], 0, s[0:1]
	global_load_dword v186, v[196:197], off
	v_lshl_add_u64 v[196:197], v[196:197], 0, s[0:1]
	global_load_dword v187, v[198:199], off
	v_lshl_add_u64 v[198:199], v[198:199], 0, s[0:1]
	global_load_dword v188, v[200:201], off
	v_lshl_add_u64 v[200:201], v[200:201], 0, s[0:1]
	ds_read_b128 v[204:207], v202 offset:272
	ds_read_b128 v[208:211], v202 offset:4368
	ds_read_b128 v[212:215], v202 offset:8464
	ds_read_b128 v[216:219], v202 offset:12560
	ds_read_b128 v[220:223], v202 offset:16656
	ds_read_b128 v[224:227], v202 offset:20752
	ds_read_b128 v[228:231], v202 offset:24848
	ds_read_b128 v[232:235], v202 offset:28944
	s_waitcnt vmcnt(56) lgkmcnt(8)
	v_fma_f32 v10, v128, v14, v10
	v_fma_f32 v11, v128, v18, v11
	v_fma_f32 v8, v128, v22, v8
	v_fma_f32 v9, v128, v26, v9
	v_fma_f32 v6, v128, v30, v6
	v_fma_f32 v7, v128, v34, v7
	v_fma_f32 v4, v128, v38, v4
	v_fma_f32 v5, v128, v42, v5
	v_fma_f32 v10, v129, v15, v10
	v_fma_f32 v11, v129, v19, v11
	v_fma_f32 v8, v129, v23, v8
	v_fma_f32 v9, v129, v27, v9
	v_fma_f32 v6, v129, v31, v6
	v_fma_f32 v7, v129, v35, v7
	v_fma_f32 v4, v129, v39, v4
	v_fma_f32 v5, v129, v43, v5
	v_fma_f32 v10, v130, v16, v10
	v_fma_f32 v11, v130, v20, v11
	v_fma_f32 v8, v130, v24, v8
	v_fma_f32 v9, v130, v28, v9
	v_fma_f32 v6, v130, v32, v6
	v_fma_f32 v7, v130, v36, v7
	v_fma_f32 v4, v130, v40, v4
	v_fma_f32 v5, v130, v44, v5
	v_fma_f32 v10, v131, v17, v10
	v_fma_f32 v11, v131, v21, v11
	v_fma_f32 v8, v131, v25, v8
	v_fma_f32 v9, v131, v29, v9
	v_fma_f32 v6, v131, v33, v6
	v_fma_f32 v7, v131, v37, v7
	v_fma_f32 v4, v131, v41, v4
	v_fma_f32 v5, v131, v45, v5
	global_load_dword v189, v[194:195], off
	global_load_dword v190, v[196:197], off
	global_load_dword v191, v[198:199], off
	global_load_dword v192, v[200:201], off
	ds_read_b128 v[14:17], v202 offset:288
	ds_read_b128 v[18:21], v202 offset:4384
	ds_read_b128 v[22:25], v202 offset:8480
	ds_read_b128 v[26:29], v202 offset:12576
	ds_read_b128 v[30:33], v202 offset:16672
	ds_read_b128 v[34:37], v202 offset:20768
	ds_read_b128 v[38:41], v202 offset:24864
	ds_read_b128 v[42:45], v202 offset:28960
	s_waitcnt vmcnt(56) lgkmcnt(8)
	v_fma_f32 v10, v132, v204, v10
	v_fma_f32 v11, v132, v208, v11
	v_fma_f32 v8, v132, v212, v8
	v_fma_f32 v9, v132, v216, v9
	v_fma_f32 v6, v132, v220, v6
	v_fma_f32 v7, v132, v224, v7
	v_fma_f32 v4, v132, v228, v4
	v_fma_f32 v5, v132, v232, v5
	v_fma_f32 v10, v133, v205, v10
	v_fma_f32 v11, v133, v209, v11
	v_fma_f32 v8, v133, v213, v8
	v_fma_f32 v9, v133, v217, v9
	v_fma_f32 v6, v133, v221, v6
	v_fma_f32 v7, v133, v225, v7
	v_fma_f32 v4, v133, v229, v4
	v_fma_f32 v5, v133, v233, v5
	v_fma_f32 v10, v134, v206, v10
	v_fma_f32 v11, v134, v210, v11
	v_fma_f32 v8, v134, v214, v8
	v_fma_f32 v9, v134, v218, v9
	v_fma_f32 v6, v134, v222, v6
	v_fma_f32 v7, v134, v226, v7
	v_fma_f32 v4, v134, v230, v4
	v_fma_f32 v5, v134, v234, v5
	v_fma_f32 v10, v135, v207, v10
	v_fma_f32 v11, v135, v211, v11
	v_fma_f32 v8, v135, v215, v8
	v_fma_f32 v9, v135, v219, v9
	v_fma_f32 v6, v135, v223, v6
	v_fma_f32 v7, v135, v227, v7
	v_fma_f32 v4, v135, v231, v4
	v_fma_f32 v5, v135, v235, v5
	ds_read_b128 v[204:207], v202 offset:304
	ds_read_b128 v[208:211], v202 offset:4400
	ds_read_b128 v[212:215], v202 offset:8496
	ds_read_b128 v[216:219], v202 offset:12592
	ds_read_b128 v[220:223], v202 offset:16688
	ds_read_b128 v[224:227], v202 offset:20784
	ds_read_b128 v[228:231], v202 offset:24880
	ds_read_b128 v[232:235], v202 offset:28976
	s_waitcnt vmcnt(52) lgkmcnt(8)
	v_fma_f32 v10, v136, v14, v10
	v_fma_f32 v11, v136, v18, v11
	v_fma_f32 v8, v136, v22, v8
	v_fma_f32 v9, v136, v26, v9
	v_fma_f32 v6, v136, v30, v6
	v_fma_f32 v7, v136, v34, v7
	v_fma_f32 v4, v136, v38, v4
	v_fma_f32 v5, v136, v42, v5
	v_fma_f32 v10, v137, v15, v10
	v_fma_f32 v11, v137, v19, v11
	v_fma_f32 v8, v137, v23, v8
	v_fma_f32 v9, v137, v27, v9
	v_fma_f32 v6, v137, v31, v6
	v_fma_f32 v7, v137, v35, v7
	v_fma_f32 v4, v137, v39, v4
	v_fma_f32 v5, v137, v43, v5
	v_fma_f32 v10, v138, v16, v10
	v_fma_f32 v11, v138, v20, v11
	v_fma_f32 v8, v138, v24, v8
	v_fma_f32 v9, v138, v28, v9
	v_fma_f32 v6, v138, v32, v6
	v_fma_f32 v7, v138, v36, v7
	v_fma_f32 v4, v138, v40, v4
	v_fma_f32 v5, v138, v44, v5
	v_fma_f32 v10, v139, v17, v10
	v_fma_f32 v11, v139, v21, v11
	v_fma_f32 v8, v139, v25, v8
	v_fma_f32 v9, v139, v29, v9
	v_fma_f32 v6, v139, v33, v6
	v_fma_f32 v7, v139, v37, v7
	v_fma_f32 v4, v139, v41, v4
	v_fma_f32 v5, v139, v45, v5
	ds_read_b128 v[14:17], v202 offset:320
	ds_read_b128 v[18:21], v202 offset:4416
	ds_read_b128 v[22:25], v202 offset:8512
	ds_read_b128 v[26:29], v202 offset:12608
	ds_read_b128 v[30:33], v202 offset:16704
	ds_read_b128 v[34:37], v202 offset:20800
	ds_read_b128 v[38:41], v202 offset:24896
	ds_read_b128 v[42:45], v202 offset:28992
	s_waitcnt vmcnt(48) lgkmcnt(8)
	v_fma_f32 v10, v140, v204, v10
	v_fma_f32 v11, v140, v208, v11
	v_fma_f32 v8, v140, v212, v8
	v_fma_f32 v9, v140, v216, v9
	v_fma_f32 v6, v140, v220, v6
	v_fma_f32 v7, v140, v224, v7
	v_fma_f32 v4, v140, v228, v4
	v_fma_f32 v5, v140, v232, v5
	v_fma_f32 v10, v141, v205, v10
	v_fma_f32 v11, v141, v209, v11
	v_fma_f32 v8, v141, v213, v8
	v_fma_f32 v9, v141, v217, v9
	v_fma_f32 v6, v141, v221, v6
	v_fma_f32 v7, v141, v225, v7
	v_fma_f32 v4, v141, v229, v4
	v_fma_f32 v5, v141, v233, v5
	v_fma_f32 v10, v142, v206, v10
	v_fma_f32 v11, v142, v210, v11
	v_fma_f32 v8, v142, v214, v8
	v_fma_f32 v9, v142, v218, v9
	v_fma_f32 v6, v142, v222, v6
	v_fma_f32 v7, v142, v226, v7
	v_fma_f32 v4, v142, v230, v4
	v_fma_f32 v5, v142, v234, v5
	v_fma_f32 v10, v143, v207, v10
	v_fma_f32 v11, v143, v211, v11
	v_fma_f32 v8, v143, v215, v8
	v_fma_f32 v9, v143, v219, v9
	v_fma_f32 v6, v143, v223, v6
	v_fma_f32 v7, v143, v227, v7
	v_fma_f32 v4, v143, v231, v4
	v_fma_f32 v5, v143, v235, v5
	ds_read_b128 v[204:207], v202 offset:336
	ds_read_b128 v[208:211], v202 offset:4432
	ds_read_b128 v[212:215], v202 offset:8528
	ds_read_b128 v[216:219], v202 offset:12624
	ds_read_b128 v[220:223], v202 offset:16720
	ds_read_b128 v[224:227], v202 offset:20816
	ds_read_b128 v[228:231], v202 offset:24912
	ds_read_b128 v[232:235], v202 offset:29008
	s_waitcnt vmcnt(44) lgkmcnt(8)
	v_fma_f32 v10, v144, v14, v10
	v_fma_f32 v11, v144, v18, v11
	v_fma_f32 v8, v144, v22, v8
	v_fma_f32 v9, v144, v26, v9
	v_fma_f32 v6, v144, v30, v6
	v_fma_f32 v7, v144, v34, v7
	v_fma_f32 v4, v144, v38, v4
	v_fma_f32 v5, v144, v42, v5
	v_fma_f32 v10, v145, v15, v10
	v_fma_f32 v11, v145, v19, v11
	v_fma_f32 v8, v145, v23, v8
	v_fma_f32 v9, v145, v27, v9
	v_fma_f32 v6, v145, v31, v6
	v_fma_f32 v7, v145, v35, v7
	v_fma_f32 v4, v145, v39, v4
	v_fma_f32 v5, v145, v43, v5
	v_fma_f32 v10, v146, v16, v10
	v_fma_f32 v11, v146, v20, v11
	v_fma_f32 v8, v146, v24, v8
	v_fma_f32 v9, v146, v28, v9
	v_fma_f32 v6, v146, v32, v6
	v_fma_f32 v7, v146, v36, v7
	v_fma_f32 v4, v146, v40, v4
	v_fma_f32 v5, v146, v44, v5
	v_fma_f32 v10, v147, v17, v10
	v_fma_f32 v11, v147, v21, v11
	v_fma_f32 v8, v147, v25, v8
	v_fma_f32 v9, v147, v29, v9
	v_fma_f32 v6, v147, v33, v6
	v_fma_f32 v7, v147, v37, v7
	v_fma_f32 v4, v147, v41, v4
	v_fma_f32 v5, v147, v45, v5
	ds_read_b128 v[14:17], v202 offset:352
	ds_read_b128 v[18:21], v202 offset:4448
	ds_read_b128 v[22:25], v202 offset:8544
	ds_read_b128 v[26:29], v202 offset:12640
	ds_read_b128 v[30:33], v202 offset:16736
	ds_read_b128 v[34:37], v202 offset:20832
	ds_read_b128 v[38:41], v202 offset:24928
	ds_read_b128 v[42:45], v202 offset:29024
	s_waitcnt vmcnt(40) lgkmcnt(8)
	v_fma_f32 v10, v148, v204, v10
	v_fma_f32 v11, v148, v208, v11
	v_fma_f32 v8, v148, v212, v8
	v_fma_f32 v9, v148, v216, v9
	v_fma_f32 v6, v148, v220, v6
	v_fma_f32 v7, v148, v224, v7
	v_fma_f32 v4, v148, v228, v4
	v_fma_f32 v5, v148, v232, v5
	v_fma_f32 v10, v149, v205, v10
	v_fma_f32 v11, v149, v209, v11
	v_fma_f32 v8, v149, v213, v8
	v_fma_f32 v9, v149, v217, v9
	v_fma_f32 v6, v149, v221, v6
	v_fma_f32 v7, v149, v225, v7
	v_fma_f32 v4, v149, v229, v4
	v_fma_f32 v5, v149, v233, v5
	v_fma_f32 v10, v150, v206, v10
	v_fma_f32 v11, v150, v210, v11
	v_fma_f32 v8, v150, v214, v8
	v_fma_f32 v9, v150, v218, v9
	v_fma_f32 v6, v150, v222, v6
	v_fma_f32 v7, v150, v226, v7
	v_fma_f32 v4, v150, v230, v4
	v_fma_f32 v5, v150, v234, v5
	v_fma_f32 v10, v151, v207, v10
	v_fma_f32 v11, v151, v211, v11
	v_fma_f32 v8, v151, v215, v8
	v_fma_f32 v9, v151, v219, v9
	v_fma_f32 v6, v151, v223, v6
	v_fma_f32 v7, v151, v227, v7
	v_fma_f32 v4, v151, v231, v4
	v_fma_f32 v5, v151, v235, v5
	ds_read_b128 v[204:207], v202 offset:368
	ds_read_b128 v[208:211], v202 offset:4464
	ds_read_b128 v[212:215], v202 offset:8560
	ds_read_b128 v[216:219], v202 offset:12656
	ds_read_b128 v[220:223], v202 offset:16752
	ds_read_b128 v[224:227], v202 offset:20848
	ds_read_b128 v[228:231], v202 offset:24944
	ds_read_b128 v[232:235], v202 offset:29040
	s_waitcnt vmcnt(36) lgkmcnt(8)
	v_fma_f32 v10, v152, v14, v10
	v_fma_f32 v11, v152, v18, v11
	v_fma_f32 v8, v152, v22, v8
	v_fma_f32 v9, v152, v26, v9
	v_fma_f32 v6, v152, v30, v6
	v_fma_f32 v7, v152, v34, v7
	v_fma_f32 v4, v152, v38, v4
	v_fma_f32 v5, v152, v42, v5
	v_fma_f32 v10, v153, v15, v10
	v_fma_f32 v11, v153, v19, v11
	v_fma_f32 v8, v153, v23, v8
	v_fma_f32 v9, v153, v27, v9
	v_fma_f32 v6, v153, v31, v6
	v_fma_f32 v7, v153, v35, v7
	v_fma_f32 v4, v153, v39, v4
	v_fma_f32 v5, v153, v43, v5
	v_fma_f32 v10, v154, v16, v10
	v_fma_f32 v11, v154, v20, v11
	v_fma_f32 v8, v154, v24, v8
	v_fma_f32 v9, v154, v28, v9
	v_fma_f32 v6, v154, v32, v6
	v_fma_f32 v7, v154, v36, v7
	v_fma_f32 v4, v154, v40, v4
	v_fma_f32 v5, v154, v44, v5
	v_fma_f32 v10, v155, v17, v10
	v_fma_f32 v11, v155, v21, v11
	v_fma_f32 v8, v155, v25, v8
	v_fma_f32 v9, v155, v29, v9
	v_fma_f32 v6, v155, v33, v6
	v_fma_f32 v7, v155, v37, v7
	v_fma_f32 v4, v155, v41, v4
	v_fma_f32 v5, v155, v45, v5
	ds_read_b128 v[14:17], v202 offset:384
	ds_read_b128 v[18:21], v202 offset:4480
	ds_read_b128 v[22:25], v202 offset:8576
	ds_read_b128 v[26:29], v202 offset:12672
	ds_read_b128 v[30:33], v202 offset:16768
	ds_read_b128 v[34:37], v202 offset:20864
	ds_read_b128 v[38:41], v202 offset:24960
	ds_read_b128 v[42:45], v202 offset:29056
	s_waitcnt vmcnt(32) lgkmcnt(8)
	v_fma_f32 v10, v156, v204, v10
	v_fma_f32 v11, v156, v208, v11
	v_fma_f32 v8, v156, v212, v8
	v_fma_f32 v9, v156, v216, v9
	v_fma_f32 v6, v156, v220, v6
	v_fma_f32 v7, v156, v224, v7
	v_fma_f32 v4, v156, v228, v4
	v_fma_f32 v5, v156, v232, v5
	v_fma_f32 v10, v157, v205, v10
	v_fma_f32 v11, v157, v209, v11
	v_fma_f32 v8, v157, v213, v8
	v_fma_f32 v9, v157, v217, v9
	v_fma_f32 v6, v157, v221, v6
	v_fma_f32 v7, v157, v225, v7
	v_fma_f32 v4, v157, v229, v4
	v_fma_f32 v5, v157, v233, v5
	v_fma_f32 v10, v158, v206, v10
	v_fma_f32 v11, v158, v210, v11
	v_fma_f32 v8, v158, v214, v8
	v_fma_f32 v9, v158, v218, v9
	v_fma_f32 v6, v158, v222, v6
	v_fma_f32 v7, v158, v226, v7
	v_fma_f32 v4, v158, v230, v4
	v_fma_f32 v5, v158, v234, v5
	v_fma_f32 v10, v159, v207, v10
	v_fma_f32 v11, v159, v211, v11
	v_fma_f32 v8, v159, v215, v8
	v_fma_f32 v9, v159, v219, v9
	v_fma_f32 v6, v159, v223, v6
	v_fma_f32 v7, v159, v227, v7
	v_fma_f32 v4, v159, v231, v4
	v_fma_f32 v5, v159, v235, v5
	ds_read_b128 v[204:207], v202 offset:400
	ds_read_b128 v[208:211], v202 offset:4496
	ds_read_b128 v[212:215], v202 offset:8592
	ds_read_b128 v[216:219], v202 offset:12688
	ds_read_b128 v[220:223], v202 offset:16784
	ds_read_b128 v[224:227], v202 offset:20880
	ds_read_b128 v[228:231], v202 offset:24976
	ds_read_b128 v[232:235], v202 offset:29072
	s_waitcnt vmcnt(28) lgkmcnt(8)
	v_fma_f32 v10, v160, v14, v10
	v_fma_f32 v11, v160, v18, v11
	v_fma_f32 v8, v160, v22, v8
	v_fma_f32 v9, v160, v26, v9
	v_fma_f32 v6, v160, v30, v6
	v_fma_f32 v7, v160, v34, v7
	v_fma_f32 v4, v160, v38, v4
	v_fma_f32 v5, v160, v42, v5
	v_fma_f32 v10, v161, v15, v10
	v_fma_f32 v11, v161, v19, v11
	v_fma_f32 v8, v161, v23, v8
	v_fma_f32 v9, v161, v27, v9
	v_fma_f32 v6, v161, v31, v6
	v_fma_f32 v7, v161, v35, v7
	v_fma_f32 v4, v161, v39, v4
	v_fma_f32 v5, v161, v43, v5
	v_fma_f32 v10, v162, v16, v10
	v_fma_f32 v11, v162, v20, v11
	v_fma_f32 v8, v162, v24, v8
	v_fma_f32 v9, v162, v28, v9
	v_fma_f32 v6, v162, v32, v6
	v_fma_f32 v7, v162, v36, v7
	v_fma_f32 v4, v162, v40, v4
	v_fma_f32 v5, v162, v44, v5
	v_fma_f32 v10, v163, v17, v10
	v_fma_f32 v11, v163, v21, v11
	v_fma_f32 v8, v163, v25, v8
	v_fma_f32 v9, v163, v29, v9
	v_fma_f32 v6, v163, v33, v6
	v_fma_f32 v7, v163, v37, v7
	v_fma_f32 v4, v163, v41, v4
	v_fma_f32 v5, v163, v45, v5
	ds_read_b128 v[14:17], v202 offset:416
	ds_read_b128 v[18:21], v202 offset:4512
	ds_read_b128 v[22:25], v202 offset:8608
	ds_read_b128 v[26:29], v202 offset:12704
	ds_read_b128 v[30:33], v202 offset:16800
	ds_read_b128 v[34:37], v202 offset:20896
	ds_read_b128 v[38:41], v202 offset:24992
	ds_read_b128 v[42:45], v202 offset:29088
	s_waitcnt vmcnt(24) lgkmcnt(8)
	v_fma_f32 v10, v164, v204, v10
	v_fma_f32 v11, v164, v208, v11
	v_fma_f32 v8, v164, v212, v8
	v_fma_f32 v9, v164, v216, v9
	v_fma_f32 v6, v164, v220, v6
	v_fma_f32 v7, v164, v224, v7
	v_fma_f32 v4, v164, v228, v4
	v_fma_f32 v5, v164, v232, v5
	v_fma_f32 v10, v165, v205, v10
	v_fma_f32 v11, v165, v209, v11
	v_fma_f32 v8, v165, v213, v8
	v_fma_f32 v9, v165, v217, v9
	v_fma_f32 v6, v165, v221, v6
	v_fma_f32 v7, v165, v225, v7
	v_fma_f32 v4, v165, v229, v4
	v_fma_f32 v5, v165, v233, v5
	v_fma_f32 v10, v166, v206, v10
	v_fma_f32 v11, v166, v210, v11
	v_fma_f32 v8, v166, v214, v8
	v_fma_f32 v9, v166, v218, v9
	v_fma_f32 v6, v166, v222, v6
	v_fma_f32 v7, v166, v226, v7
	v_fma_f32 v4, v166, v230, v4
	v_fma_f32 v5, v166, v234, v5
	v_fma_f32 v10, v167, v207, v10
	v_fma_f32 v11, v167, v211, v11
	v_fma_f32 v8, v167, v215, v8
	v_fma_f32 v9, v167, v219, v9
	v_fma_f32 v6, v167, v223, v6
	v_fma_f32 v7, v167, v227, v7
	v_fma_f32 v4, v167, v231, v4
	v_fma_f32 v5, v167, v235, v5
	ds_read_b128 v[204:207], v202 offset:432
	ds_read_b128 v[208:211], v202 offset:4528
	ds_read_b128 v[212:215], v202 offset:8624
	ds_read_b128 v[216:219], v202 offset:12720
	ds_read_b128 v[220:223], v202 offset:16816
	ds_read_b128 v[224:227], v202 offset:20912
	ds_read_b128 v[228:231], v202 offset:25008
	ds_read_b128 v[232:235], v202 offset:29104
	s_waitcnt vmcnt(20) lgkmcnt(8)
	v_fma_f32 v10, v168, v14, v10
	v_fma_f32 v11, v168, v18, v11
	v_fma_f32 v8, v168, v22, v8
	v_fma_f32 v9, v168, v26, v9
	v_fma_f32 v6, v168, v30, v6
	v_fma_f32 v7, v168, v34, v7
	v_fma_f32 v4, v168, v38, v4
	v_fma_f32 v5, v168, v42, v5
	v_fma_f32 v10, v169, v15, v10
	v_fma_f32 v11, v169, v19, v11
	v_fma_f32 v8, v169, v23, v8
	v_fma_f32 v9, v169, v27, v9
	v_fma_f32 v6, v169, v31, v6
	v_fma_f32 v7, v169, v35, v7
	v_fma_f32 v4, v169, v39, v4
	v_fma_f32 v5, v169, v43, v5
	v_fma_f32 v10, v170, v16, v10
	v_fma_f32 v11, v170, v20, v11
	v_fma_f32 v8, v170, v24, v8
	v_fma_f32 v9, v170, v28, v9
	v_fma_f32 v6, v170, v32, v6
	v_fma_f32 v7, v170, v36, v7
	v_fma_f32 v4, v170, v40, v4
	v_fma_f32 v5, v170, v44, v5
	v_fma_f32 v10, v171, v17, v10
	v_fma_f32 v11, v171, v21, v11
	v_fma_f32 v8, v171, v25, v8
	v_fma_f32 v9, v171, v29, v9
	v_fma_f32 v6, v171, v33, v6
	v_fma_f32 v7, v171, v37, v7
	v_fma_f32 v4, v171, v41, v4
	v_fma_f32 v5, v171, v45, v5
	ds_read_b128 v[14:17], v202 offset:448
	ds_read_b128 v[18:21], v202 offset:4544
	ds_read_b128 v[22:25], v202 offset:8640
	ds_read_b128 v[26:29], v202 offset:12736
	ds_read_b128 v[30:33], v202 offset:16832
	ds_read_b128 v[34:37], v202 offset:20928
	ds_read_b128 v[38:41], v202 offset:25024
	ds_read_b128 v[42:45], v202 offset:29120
	s_waitcnt vmcnt(16) lgkmcnt(8)
	v_fma_f32 v10, v172, v204, v10
	v_fma_f32 v11, v172, v208, v11
	v_fma_f32 v8, v172, v212, v8
	v_fma_f32 v9, v172, v216, v9
	v_fma_f32 v6, v172, v220, v6
	v_fma_f32 v7, v172, v224, v7
	v_fma_f32 v4, v172, v228, v4
	v_fma_f32 v5, v172, v232, v5
	v_fma_f32 v10, v173, v205, v10
	v_fma_f32 v11, v173, v209, v11
	v_fma_f32 v8, v173, v213, v8
	v_fma_f32 v9, v173, v217, v9
	v_fma_f32 v6, v173, v221, v6
	v_fma_f32 v7, v173, v225, v7
	v_fma_f32 v4, v173, v229, v4
	v_fma_f32 v5, v173, v233, v5
	v_fma_f32 v10, v174, v206, v10
	v_fma_f32 v11, v174, v210, v11
	v_fma_f32 v8, v174, v214, v8
	v_fma_f32 v9, v174, v218, v9
	v_fma_f32 v6, v174, v222, v6
	v_fma_f32 v7, v174, v226, v7
	v_fma_f32 v4, v174, v230, v4
	v_fma_f32 v5, v174, v234, v5
	v_fma_f32 v10, v175, v207, v10
	v_fma_f32 v11, v175, v211, v11
	v_fma_f32 v8, v175, v215, v8
	v_fma_f32 v9, v175, v219, v9
	v_fma_f32 v6, v175, v223, v6
	v_fma_f32 v7, v175, v227, v7
	v_fma_f32 v4, v175, v231, v4
	v_fma_f32 v5, v175, v235, v5
	ds_read_b128 v[204:207], v202 offset:464
	ds_read_b128 v[208:211], v202 offset:4560
	ds_read_b128 v[212:215], v202 offset:8656
	ds_read_b128 v[216:219], v202 offset:12752
	ds_read_b128 v[220:223], v202 offset:16848
	ds_read_b128 v[224:227], v202 offset:20944
	ds_read_b128 v[228:231], v202 offset:25040
	ds_read_b128 v[232:235], v202 offset:29136
	s_waitcnt vmcnt(12) lgkmcnt(8)
	v_fma_f32 v10, v176, v14, v10
	v_fma_f32 v11, v176, v18, v11
	v_fma_f32 v8, v176, v22, v8
	v_fma_f32 v9, v176, v26, v9
	v_fma_f32 v6, v176, v30, v6
	v_fma_f32 v7, v176, v34, v7
	v_fma_f32 v4, v176, v38, v4
	v_fma_f32 v5, v176, v42, v5
	v_fma_f32 v10, v177, v15, v10
	v_fma_f32 v11, v177, v19, v11
	v_fma_f32 v8, v177, v23, v8
	v_fma_f32 v9, v177, v27, v9
	v_fma_f32 v6, v177, v31, v6
	v_fma_f32 v7, v177, v35, v7
	v_fma_f32 v4, v177, v39, v4
	v_fma_f32 v5, v177, v43, v5
	v_fma_f32 v10, v178, v16, v10
	v_fma_f32 v11, v178, v20, v11
	v_fma_f32 v8, v178, v24, v8
	v_fma_f32 v9, v178, v28, v9
	v_fma_f32 v6, v178, v32, v6
	v_fma_f32 v7, v178, v36, v7
	v_fma_f32 v4, v178, v40, v4
	v_fma_f32 v5, v178, v44, v5
	v_fma_f32 v10, v180, v17, v10
	v_fma_f32 v11, v180, v21, v11
	v_fma_f32 v8, v180, v25, v8
	v_fma_f32 v9, v180, v29, v9
	v_fma_f32 v6, v180, v33, v6
	v_fma_f32 v7, v180, v37, v7
	v_fma_f32 v4, v180, v41, v4
	v_fma_f32 v5, v180, v45, v5
	ds_read_b128 v[14:17], v202 offset:480
	ds_read_b128 v[18:21], v202 offset:4576
	ds_read_b128 v[22:25], v202 offset:8672
	ds_read_b128 v[26:29], v202 offset:12768
	ds_read_b128 v[30:33], v202 offset:16864
	ds_read_b128 v[34:37], v202 offset:20960
	ds_read_b128 v[38:41], v202 offset:25056
	ds_read_b128 v[42:45], v202 offset:29152
	s_waitcnt vmcnt(8) lgkmcnt(8)
	v_fma_f32 v10, v181, v204, v10
	v_fma_f32 v11, v181, v208, v11
	v_fma_f32 v8, v181, v212, v8
	v_fma_f32 v9, v181, v216, v9
	v_fma_f32 v6, v181, v220, v6
	v_fma_f32 v7, v181, v224, v7
	v_fma_f32 v4, v181, v228, v4
	v_fma_f32 v5, v181, v232, v5
	v_fma_f32 v10, v182, v205, v10
	v_fma_f32 v11, v182, v209, v11
	v_fma_f32 v8, v182, v213, v8
	v_fma_f32 v9, v182, v217, v9
	v_fma_f32 v6, v182, v221, v6
	v_fma_f32 v7, v182, v225, v7
	v_fma_f32 v4, v182, v229, v4
	v_fma_f32 v5, v182, v233, v5
	v_fma_f32 v10, v183, v206, v10
	v_fma_f32 v11, v183, v210, v11
	v_fma_f32 v8, v183, v214, v8
	v_fma_f32 v9, v183, v218, v9
	v_fma_f32 v6, v183, v222, v6
	v_fma_f32 v7, v183, v226, v7
	v_fma_f32 v4, v183, v230, v4
	v_fma_f32 v5, v183, v234, v5
	v_fma_f32 v10, v184, v207, v10
	v_fma_f32 v11, v184, v211, v11
	v_fma_f32 v8, v184, v215, v8
	v_fma_f32 v9, v184, v219, v9
	v_fma_f32 v6, v184, v223, v6
	v_fma_f32 v7, v184, v227, v7
	v_fma_f32 v4, v184, v231, v4
	v_fma_f32 v5, v184, v235, v5
	ds_read_b128 v[204:207], v202 offset:496
	ds_read_b128 v[208:211], v202 offset:4592
	ds_read_b128 v[212:215], v202 offset:8688
	ds_read_b128 v[216:219], v202 offset:12784
	ds_read_b128 v[220:223], v202 offset:16880
	ds_read_b128 v[224:227], v202 offset:20976
	ds_read_b128 v[228:231], v202 offset:25072
	ds_read_b128 v[232:235], v202 offset:29168
	s_waitcnt vmcnt(4) lgkmcnt(8)
	v_fma_f32 v10, v185, v14, v10
	v_fma_f32 v11, v185, v18, v11
	v_fma_f32 v8, v185, v22, v8
	v_fma_f32 v9, v185, v26, v9
	v_fma_f32 v6, v185, v30, v6
	v_fma_f32 v7, v185, v34, v7
	v_fma_f32 v4, v185, v38, v4
	v_fma_f32 v5, v185, v42, v5
	v_fma_f32 v10, v186, v15, v10
	v_fma_f32 v11, v186, v19, v11
	v_fma_f32 v8, v186, v23, v8
	v_fma_f32 v9, v186, v27, v9
	v_fma_f32 v6, v186, v31, v6
	v_fma_f32 v7, v186, v35, v7
	v_fma_f32 v4, v186, v39, v4
	v_fma_f32 v5, v186, v43, v5
	v_fma_f32 v10, v187, v16, v10
	v_fma_f32 v11, v187, v20, v11
	v_fma_f32 v8, v187, v24, v8
	v_fma_f32 v9, v187, v28, v9
	v_fma_f32 v6, v187, v32, v6
	v_fma_f32 v7, v187, v36, v7
	v_fma_f32 v4, v187, v40, v4
	v_fma_f32 v5, v187, v44, v5
	v_fma_f32 v10, v188, v17, v10
	v_fma_f32 v11, v188, v21, v11
	v_fma_f32 v8, v188, v25, v8
	v_fma_f32 v9, v188, v29, v9
	v_fma_f32 v6, v188, v33, v6
	v_fma_f32 v7, v188, v37, v7
	v_fma_f32 v4, v188, v41, v4
	v_fma_f32 v5, v188, v45, v5
	s_waitcnt vmcnt(0) lgkmcnt(0)
	v_fma_f32 v10, v189, v204, v10
	v_fma_f32 v11, v189, v208, v11
	v_fma_f32 v8, v189, v212, v8
	v_fma_f32 v9, v189, v216, v9
	v_fma_f32 v6, v189, v220, v6
	v_fma_f32 v7, v189, v224, v7
	v_fma_f32 v4, v189, v228, v4
	v_fma_f32 v5, v189, v232, v5
	v_fma_f32 v10, v190, v205, v10
	v_fma_f32 v11, v190, v209, v11
	v_fma_f32 v8, v190, v213, v8
	v_fma_f32 v9, v190, v217, v9
	v_fma_f32 v6, v190, v221, v6
	v_fma_f32 v7, v190, v225, v7
	v_fma_f32 v4, v190, v229, v4
	v_fma_f32 v5, v190, v233, v5
	v_fma_f32 v10, v191, v206, v10
	v_fma_f32 v11, v191, v210, v11
	v_fma_f32 v8, v191, v214, v8
	v_fma_f32 v9, v191, v218, v9
	v_fma_f32 v6, v191, v222, v6
	v_fma_f32 v7, v191, v226, v7
	v_fma_f32 v4, v191, v230, v4
	v_fma_f32 v5, v191, v234, v5
	v_fma_f32 v10, v192, v207, v10
	v_fma_f32 v11, v192, v211, v11
	v_fma_f32 v8, v192, v215, v8
	v_fma_f32 v9, v192, v219, v9
	v_fma_f32 v6, v192, v223, v6
	v_fma_f32 v7, v192, v227, v7
	v_fma_f32 v4, v192, v231, v4
	v_fma_f32 v5, v192, v235, v5
	s_cmp_eq_u32 s9, 0
	v_mov_b32_e32 v12, 0
	s_cbranch_scc0 .LBB0_19
	s_mul_i32 s0, s8, 0x2400
	v_add_u32_e32 v12, s0, v2
	v_readlane_b32 s36, v249, 0
	v_ashrrev_i32_e32 v13, 31, v12
	v_readlane_b32 s42, v249, 6
	v_readlane_b32 s43, v249, 7
	v_readlane_b32 s37, v249, 1
	v_readlane_b32 s38, v249, 2
	v_lshl_add_u64 v[12:13], v[12:13], 2, s[42:43]
	global_load_dword v12, v[12:13], off
	v_readlane_b32 s39, v249, 3
	v_readlane_b32 s40, v249, 4
	v_readlane_b32 s41, v249, 5
	s_branch .LBB0_19
